# kept version with the mid-cluster s_setprio 0/1 flip pairs removed from the in-proj and out-proj K-loops (s_setprio A/B per asm guide 6.3)
# speedup vs baseline: 1.0312x; 1.0176x over previous
; #define PG8_STAGE(bufoff, gbase, voff) do { _Pragma("unroll") for (int _i = 0; _i < 2; ++_i) \
;         __builtin_amdgcn_global_load_lds((const unsigned*)((const char*)(gbase) + (voff)[_i]), (PG8_LAS unsigned*)(lds + (bufoff) + ldsw + _i * 8192), 16, 0, 0); } while (0)
; #define PG8_LDA(dst, b, h) do { _Pragma("unroll") for (int m = 0; m < 4; ++m) _Pragma("unroll") for (int k = 0; k < 2; ++k) dst[m][k] = *(const PG8_LAS bf16x8*)(lds + PG8_SA(b, h) + aoff + m * 2048 + k * 1024); } while (0)
; #define PG8_LDB(dst, b, h) do { _Pragma("unroll") for (int n = 0; n < 2; ++n) _Pragma("unroll") for (int k = 0; k < 2; ++k) dst[n][k] = *(const PG8_LAS bf16x8*)(lds + PG8_SB(b, h) + boff + n * 2048 + k * 1024); } while (0)
; #define PG8_MMA(ai, bj, At, Bt) do { __builtin_amdgcn_s_setprio(1); _Pragma("unroll") for (int m = 0; m < 4; ++m) _Pragma("unroll") for (int n = 0; n < 2; ++n) _Pragma("unroll") for (int k = 0; k < 2; ++k) \
;         acc[ai][bj][m][n] = __builtin_amdgcn_mfma_f32_16x16x32_bf16(Bt[n][k], At[m][k], acc[ai][bj][m][n], 0, 0, 0); __builtin_amdgcn_s_setprio(0); } while (0)
; #define PG8_WAIT_V(n) asm volatile("s_waitcnt vmcnt(" #n ")" ::: "memory")
; #define PG8_WAIT_L(n) asm volatile("s_waitcnt lgkmcnt(" #n ")" ::: "memory")
; #define PG8_BAR __builtin_amdgcn_s_barrier()
; #define PG8_SCHED __builtin_amdgcn_sched_barrier(0)
; template <class Epi, class Sched, bool ALIGN_EPI = false, bool SP2 = false>
; __device__ __forceinline__ void gemm_phase(PG8_LAS unsigned char* lds, const Gemm g, const Sched& S, const Epi& E) {
;     ...
;             PG8_LDB(B0, 0, 0); PG8_LDB(B1, 0, 1); PG8_SCHED; PG8_LDA(At, 0, 0); PG8_STAGE(PG8_SA(1, 1), a1 + hstep, voffA);
;             PG8_WAIT_V(8); PG8_WAIT_L(0); PG8_BAR; PG8_MMA(0, 0, At, B0); PG8_MMA(0, 1, At, B1); PG8_BAR; PG8_SCHED;
;             PG8_LDA(At, 0, 1); PG8_STAGE(PG8_SB(0, 0), b2, voffB); PG8_STAGE(PG8_SB(0, 1), b2 + hstep, voffB); PG8_STAGE(PG8_SA(0, 0), a2, voffA);
;             PG8_WAIT_V(8); PG8_WAIT_L(0); PG8_BAR; PG8_MMA(1, 0, At, B0); PG8_MMA(1, 1, At, B1); PG8_BAR; PG8_SCHED;
.LBB0_411:
	ds_read_b128 v[130:133], v218
	ds_read_b128 v[134:137], v218 offset:1024
	ds_read_b128 v[138:141], v218 offset:2048
	ds_read_b128 v[142:145], v218 offset:3072
	ds_read_b128 v[146:149], v219
	ds_read_b128 v[150:153], v219 offset:1024
	ds_read_b128 v[154:157], v219 offset:2048
	ds_read_b128 v[158:161], v219 offset:3072
	s_add_u32 s6, s4, 0xfffc0080
	s_addc_u32 s7, s5, -1
	s_cmp_eq_u32 s37, 12
	s_cselect_b32 s45, s0, s7
	s_cselect_b32 s44, s1, s6
	s_cselect_b32 s7, s9, s35
	s_cselect_b32 s6, s12, s33
	v_lshl_add_u64 v[226:227], s[4:5], 0, v[188:189]
	s_add_i32 m0, s51, 0xc000
	s_waitcnt vmcnt(0)
	ds_read_b128 v[162:165], v220
	ds_read_b128 v[166:169], v220 offset:1024
	ds_read_b128 v[170:173], v220 offset:2048
	ds_read_b128 v[196:199], v220 offset:3072
	ds_read_b128 v[200:203], v220 offset:4096
	ds_read_b128 v[204:207], v220 offset:5120
	ds_read_b128 v[208:211], v220 offset:6144
	ds_read_b128 v[212:215], v220 offset:7168
	global_load_lds_dwordx4 v[226:227], off
	v_lshl_add_u64 v[226:227], s[4:5], 0, v[190:191]
	s_add_i32 m0, s51, 0xe000
	s_nop 0
	global_load_lds_dwordx4 v[226:227], off
	s_waitcnt vmcnt(8)
	s_waitcnt lgkmcnt(0)
	s_barrier
	s_setprio 1
	s_waitcnt lgkmcnt(0)
	v_mfma_f32_16x16x32_bf16 v[126:129], v[130:133], v[162:165], v[126:129]
	v_mfma_f32_16x16x32_bf16 v[122:125], v[138:141], v[162:165], v[122:125]
	v_mfma_f32_16x16x32_bf16 v[110:113], v[130:133], v[170:173], v[110:113]
	v_mfma_f32_16x16x32_bf16 v[106:109], v[138:141], v[170:173], v[106:109]
	v_mfma_f32_16x16x32_bf16 v[94:97], v[130:133], v[200:203], v[94:97]
	v_mfma_f32_16x16x32_bf16 v[90:93], v[138:141], v[200:203], v[90:93]
	v_mfma_f32_16x16x32_bf16 v[78:81], v[130:133], v[208:211], v[78:81]
	v_mfma_f32_16x16x32_bf16 v[74:77], v[138:141], v[208:211], v[74:77]
	v_mfma_f32_16x16x32_bf16 v[126:129], v[134:137], v[166:169], v[126:129]
	v_mfma_f32_16x16x32_bf16 v[122:125], v[142:145], v[166:169], v[122:125]
	v_mfma_f32_16x16x32_bf16 v[110:113], v[134:137], v[196:199], v[110:113]
	v_mfma_f32_16x16x32_bf16 v[106:109], v[142:145], v[196:199], v[106:109]
	v_mfma_f32_16x16x32_bf16 v[94:97], v[134:137], v[204:207], v[94:97]
	v_mfma_f32_16x16x32_bf16 v[90:93], v[142:145], v[204:207], v[90:93]
	v_mfma_f32_16x16x32_bf16 v[78:81], v[134:137], v[212:215], v[78:81]
	v_mfma_f32_16x16x32_bf16 v[74:77], v[142:145], v[212:215], v[74:77]
	v_mfma_f32_16x16x32_bf16 v[118:121], v[146:149], v[162:165], v[118:121]
	v_mfma_f32_16x16x32_bf16 v[114:117], v[154:157], v[162:165], v[114:117]
	v_mfma_f32_16x16x32_bf16 v[102:105], v[146:149], v[170:173], v[102:105]
	v_mfma_f32_16x16x32_bf16 v[98:101], v[154:157], v[170:173], v[98:101]
	v_mfma_f32_16x16x32_bf16 v[86:89], v[146:149], v[200:203], v[86:89]
	v_mfma_f32_16x16x32_bf16 v[82:85], v[154:157], v[200:203], v[82:85]
	v_mfma_f32_16x16x32_bf16 v[70:73], v[146:149], v[208:211], v[70:73]
	v_mfma_f32_16x16x32_bf16 v[66:69], v[154:157], v[208:211], v[66:69]
	v_mfma_f32_16x16x32_bf16 v[118:121], v[150:153], v[166:169], v[118:121]
	v_mfma_f32_16x16x32_bf16 v[114:117], v[158:161], v[166:169], v[114:117]
	v_mfma_f32_16x16x32_bf16 v[102:105], v[150:153], v[196:199], v[102:105]
	v_mfma_f32_16x16x32_bf16 v[98:101], v[158:161], v[196:199], v[98:101]
	v_mfma_f32_16x16x32_bf16 v[86:89], v[150:153], v[204:207], v[86:89]
	v_mfma_f32_16x16x32_bf16 v[82:85], v[158:161], v[204:207], v[82:85]
	v_mfma_f32_16x16x32_bf16 v[70:73], v[150:153], v[212:215], v[70:73]
	v_mfma_f32_16x16x32_bf16 v[66:69], v[158:161], v[212:215], v[66:69]
	s_setprio 0
	s_barrier
	s_add_i32 s43, s86, s50
	v_lshl_add_u64 v[226:227], s[6:7], 0, v[178:179]
	s_mov_b32 m0, s43
	ds_read_b128 v[162:165], v220 offset:16384
	ds_read_b128 v[166:169], v220 offset:17408
	ds_read_b128 v[170:173], v220 offset:18432
	ds_read_b128 v[196:199], v220 offset:19456
	ds_read_b128 v[200:203], v220 offset:20480
	ds_read_b128 v[204:207], v220 offset:21504
	ds_read_b128 v[208:211], v220 offset:22528
	ds_read_b128 v[212:215], v220 offset:23552
	global_load_lds_dwordx4 v[226:227], off
	s_add_i32 m0, s43, 0x2000
	s_add_u32 s46, s6, 0x40000
	v_lshl_add_u64 v[228:229], s[6:7], 0, v[182:183]
	s_addc_u32 s47, s7, 0
	s_add_i32 s43, s87, s50
	global_load_lds_dwordx4 v[228:229], off
	v_lshl_add_u64 v[230:231], s[46:47], 0, v[178:179]
	s_mov_b32 m0, s43
	v_lshl_add_u64 v[232:233], s[44:45], 0, v[180:181]
	global_load_lds_dwordx4 v[230:231], off
	v_lshl_add_u64 v[230:231], s[46:47], 0, v[182:183]
	s_add_i32 m0, s43, 0x2000
	s_nop 0
	global_load_lds_dwordx4 v[230:231], off
	v_lshl_add_u64 v[230:231], s[44:45], 0, v[176:177]
	s_mov_b32 m0, s51
	s_nop 0
	global_load_lds_dwordx4 v[230:231], off
	s_mov_b32 m0, s52
	s_nop 0
	global_load_lds_dwordx4 v[232:233], off
	s_waitcnt vmcnt(8)
	s_waitcnt lgkmcnt(0)
	s_barrier
; #define PG8_STAGE(bufoff, gbase, voff) do { _Pragma("unroll") for (int _i = 0; _i < 2; ++_i) \
;         __builtin_amdgcn_global_load_lds((const unsigned*)((const char*)(gbase) + (voff)[_i]), (PG8_LAS unsigned*)(lds + (bufoff) + ldsw + _i * 8192), 16, 0, 0); } while (0)
; #define PG8_LDA(dst, b, h) do { _Pragma("unroll") for (int m = 0; m < 4; ++m) _Pragma("unroll") for (int k = 0; k < 2; ++k) dst[m][k] = *(const PG8_LAS bf16x8*)(lds + PG8_SA(b, h) + aoff + m * 2048 + k * 1024); } while (0)
; #define PG8_LDB(dst, b, h) do { _Pragma("unroll") for (int n = 0; n < 2; ++n) _Pragma("unroll") for (int k = 0; k < 2; ++k) dst[n][k] = *(const PG8_LAS bf16x8*)(lds + PG8_SB(b, h) + boff + n * 2048 + k * 1024); } while (0)
; #define PG8_MMA(ai, bj, At, Bt) do { __builtin_amdgcn_s_setprio(1); _Pragma("unroll") for (int m = 0; m < 4; ++m) _Pragma("unroll") for (int n = 0; n < 2; ++n) _Pragma("unroll") for (int k = 0; k < 2; ++k) \
;         acc[ai][bj][m][n] = __builtin_amdgcn_mfma_f32_16x16x32_bf16(Bt[n][k], At[m][k], acc[ai][bj][m][n], 0, 0, 0); __builtin_amdgcn_s_setprio(0); } while (0)
; #define PG8_WAIT_V(n) asm volatile("s_waitcnt vmcnt(" #n ")" ::: "memory")
; #define PG8_WAIT_L(n) asm volatile("s_waitcnt lgkmcnt(" #n ")" ::: "memory")
; #define PG8_BAR __builtin_amdgcn_s_barrier()
; #define PG8_SCHED __builtin_amdgcn_sched_barrier(0)
; template <class Epi, class Sched, bool ALIGN_EPI = false, bool SP2 = false>
; __device__ __forceinline__ void gemm_phase(PG8_LAS unsigned char* lds, const Gemm g, const Sched& S, const Epi& E) {
;     ...
;             PG8_WAIT_V(8); PG8_WAIT_L(0); PG8_BAR; PG8_MMA(1, 0, At, B0); PG8_MMA(1, 1, At, B1); PG8_BAR; PG8_SCHED;
;             PG8_LDB(B0, 1, 0); PG8_LDB(B1, 1, 1); PG8_SCHED; PG8_LDA(At, 1, 0); PG8_STAGE(PG8_SA(0, 1), a2 + hstep, voffA);
;             PG8_WAIT_V(8); PG8_WAIT_L(0); PG8_BAR; PG8_MMA(0, 0, At, B0); PG8_MMA(0, 1, At, B1); PG8_BAR; PG8_SCHED;
	s_setprio 1
	s_waitcnt lgkmcnt(0)
	v_mfma_f32_16x16x32_bf16 v[62:65], v[130:133], v[162:165], v[62:65]
	v_mfma_f32_16x16x32_bf16 v[58:61], v[138:141], v[162:165], v[58:61]
	v_mfma_f32_16x16x32_bf16 v[46:49], v[130:133], v[170:173], v[46:49]
	v_mfma_f32_16x16x32_bf16 v[42:45], v[138:141], v[170:173], v[42:45]
	v_mfma_f32_16x16x32_bf16 v[30:33], v[130:133], v[200:203], v[30:33]
	v_mfma_f32_16x16x32_bf16 v[26:29], v[138:141], v[200:203], v[26:29]
	v_mfma_f32_16x16x32_bf16 v[14:17], v[130:133], v[208:211], v[14:17]
	v_mfma_f32_16x16x32_bf16 v[10:13], v[138:141], v[208:211], v[10:13]
	v_mfma_f32_16x16x32_bf16 v[62:65], v[134:137], v[166:169], v[62:65]
	v_mfma_f32_16x16x32_bf16 v[58:61], v[142:145], v[166:169], v[58:61]
	v_mfma_f32_16x16x32_bf16 v[46:49], v[134:137], v[196:199], v[46:49]
	v_mfma_f32_16x16x32_bf16 v[42:45], v[142:145], v[196:199], v[42:45]
	v_mfma_f32_16x16x32_bf16 v[30:33], v[134:137], v[204:207], v[30:33]
	v_mfma_f32_16x16x32_bf16 v[26:29], v[142:145], v[204:207], v[26:29]
	v_mfma_f32_16x16x32_bf16 v[14:17], v[134:137], v[212:215], v[14:17]
	v_mfma_f32_16x16x32_bf16 v[10:13], v[142:145], v[212:215], v[10:13]
	v_mfma_f32_16x16x32_bf16 v[54:57], v[146:149], v[162:165], v[54:57]
	v_mfma_f32_16x16x32_bf16 v[50:53], v[154:157], v[162:165], v[50:53]
	v_mfma_f32_16x16x32_bf16 v[38:41], v[146:149], v[170:173], v[38:41]
	v_mfma_f32_16x16x32_bf16 v[34:37], v[154:157], v[170:173], v[34:37]
	v_mfma_f32_16x16x32_bf16 v[22:25], v[146:149], v[200:203], v[22:25]
	v_mfma_f32_16x16x32_bf16 v[18:21], v[154:157], v[200:203], v[18:21]
	v_mfma_f32_16x16x32_bf16 v[6:9], v[146:149], v[208:211], v[6:9]
	v_mfma_f32_16x16x32_bf16 v[2:5], v[154:157], v[208:211], v[2:5]
	v_mfma_f32_16x16x32_bf16 v[54:57], v[150:153], v[166:169], v[54:57]
	v_mfma_f32_16x16x32_bf16 v[50:53], v[158:161], v[166:169], v[50:53]
	v_mfma_f32_16x16x32_bf16 v[38:41], v[150:153], v[196:199], v[38:41]
	v_mfma_f32_16x16x32_bf16 v[34:37], v[158:161], v[196:199], v[34:37]
	v_mfma_f32_16x16x32_bf16 v[22:25], v[150:153], v[204:207], v[22:25]
	v_mfma_f32_16x16x32_bf16 v[18:21], v[158:161], v[204:207], v[18:21]
	v_mfma_f32_16x16x32_bf16 v[6:9], v[150:153], v[212:215], v[6:9]
	v_mfma_f32_16x16x32_bf16 v[2:5], v[158:161], v[212:215], v[2:5]
	s_setprio 0
	s_barrier
	s_add_i32 s43, 0, 0x18000
	s_add_i32 s46, 0, 0x1c000
	v_add_u32_e32 v142, s43, v217
	v_add_u32_e32 v158, s46, v217
	ds_read_b128 v[130:133], v142
	ds_read_b128 v[134:137], v142 offset:1024
	ds_read_b128 v[138:141], v142 offset:2048
	ds_read_b128 v[142:145], v142 offset:3072
	ds_read_b128 v[146:149], v158
	ds_read_b128 v[150:153], v158 offset:1024
	ds_read_b128 v[154:157], v158 offset:2048
	ds_read_b128 v[158:161], v158 offset:3072
	s_add_u32 s44, s44, 0x40000
	s_addc_u32 s45, s45, 0
	s_mov_b32 m0, s53
	v_lshl_add_u64 v[234:235], s[44:45], 0, v[176:177]
	ds_read_b128 v[162:165], v220 offset:32768
	ds_read_b128 v[166:169], v220 offset:33792
	ds_read_b128 v[170:173], v220 offset:34816
	ds_read_b128 v[196:199], v220 offset:35840
	ds_read_b128 v[200:203], v220 offset:36864
	ds_read_b128 v[204:207], v220 offset:37888
	ds_read_b128 v[208:211], v220 offset:38912
	ds_read_b128 v[212:215], v220 offset:39936
	global_load_lds_dwordx4 v[234:235], off
	v_lshl_add_u64 v[234:235], s[44:45], 0, v[180:181]
	s_mov_b32 m0, s54
	s_nop 0
	global_load_lds_dwordx4 v[234:235], off
	s_waitcnt vmcnt(8)
	s_waitcnt lgkmcnt(0)
	s_barrier
	s_setprio 1
	s_waitcnt lgkmcnt(0)
	v_mfma_f32_16x16x32_bf16 v[126:129], v[130:133], v[162:165], v[126:129]
	v_mfma_f32_16x16x32_bf16 v[122:125], v[138:141], v[162:165], v[122:125]
	v_mfma_f32_16x16x32_bf16 v[110:113], v[130:133], v[170:173], v[110:113]
	v_mfma_f32_16x16x32_bf16 v[106:109], v[138:141], v[170:173], v[106:109]
	v_mfma_f32_16x16x32_bf16 v[94:97], v[130:133], v[200:203], v[94:97]
	v_mfma_f32_16x16x32_bf16 v[90:93], v[138:141], v[200:203], v[90:93]
	v_mfma_f32_16x16x32_bf16 v[78:81], v[130:133], v[208:211], v[78:81]
	v_mfma_f32_16x16x32_bf16 v[74:77], v[138:141], v[208:211], v[74:77]
	v_mfma_f32_16x16x32_bf16 v[126:129], v[134:137], v[166:169], v[126:129]
	v_mfma_f32_16x16x32_bf16 v[122:125], v[142:145], v[166:169], v[122:125]
	v_mfma_f32_16x16x32_bf16 v[110:113], v[134:137], v[196:199], v[110:113]
	v_mfma_f32_16x16x32_bf16 v[106:109], v[142:145], v[196:199], v[106:109]
	v_mfma_f32_16x16x32_bf16 v[94:97], v[134:137], v[204:207], v[94:97]
	v_mfma_f32_16x16x32_bf16 v[90:93], v[142:145], v[204:207], v[90:93]
	v_mfma_f32_16x16x32_bf16 v[78:81], v[134:137], v[212:215], v[78:81]
	v_mfma_f32_16x16x32_bf16 v[74:77], v[142:145], v[212:215], v[74:77]
	v_mfma_f32_16x16x32_bf16 v[118:121], v[146:149], v[162:165], v[118:121]
	v_mfma_f32_16x16x32_bf16 v[114:117], v[154:157], v[162:165], v[114:117]
	v_mfma_f32_16x16x32_bf16 v[102:105], v[146:149], v[170:173], v[102:105]
	v_mfma_f32_16x16x32_bf16 v[98:101], v[154:157], v[170:173], v[98:101]
	v_mfma_f32_16x16x32_bf16 v[86:89], v[146:149], v[200:203], v[86:89]
	v_mfma_f32_16x16x32_bf16 v[82:85], v[154:157], v[200:203], v[82:85]
	v_mfma_f32_16x16x32_bf16 v[70:73], v[146:149], v[208:211], v[70:73]
	v_mfma_f32_16x16x32_bf16 v[66:69], v[154:157], v[208:211], v[66:69]
	v_mfma_f32_16x16x32_bf16 v[118:121], v[150:153], v[166:169], v[118:121]
	v_mfma_f32_16x16x32_bf16 v[114:117], v[158:161], v[166:169], v[114:117]
	v_mfma_f32_16x16x32_bf16 v[102:105], v[150:153], v[196:199], v[102:105]
	v_mfma_f32_16x16x32_bf16 v[98:101], v[158:161], v[196:199], v[98:101]
	v_mfma_f32_16x16x32_bf16 v[86:89], v[150:153], v[204:207], v[86:89]
	v_mfma_f32_16x16x32_bf16 v[82:85], v[158:161], v[204:207], v[82:85]
	v_mfma_f32_16x16x32_bf16 v[70:73], v[150:153], v[212:215], v[70:73]
	v_mfma_f32_16x16x32_bf16 v[66:69], v[158:161], v[212:215], v[66:69]
	s_setprio 0
	s_barrier
; #define PG8_STAGE(bufoff, gbase, voff) do { _Pragma("unroll") for (int _i = 0; _i < 2; ++_i) \
;         __builtin_amdgcn_global_load_lds((const unsigned*)((const char*)(gbase) + (voff)[_i]), (PG8_LAS unsigned*)(lds + (bufoff) + ldsw + _i * 8192), 16, 0, 0); } while (0)
; #define PG8_LDA(dst, b, h) do { _Pragma("unroll") for (int m = 0; m < 4; ++m) _Pragma("unroll") for (int k = 0; k < 2; ++k) dst[m][k] = *(const PG8_LAS bf16x8*)(lds + PG8_SA(b, h) + aoff + m * 2048 + k * 1024); } while (0)
; #define PG8_MMA(ai, bj, At, Bt) do { __builtin_amdgcn_s_setprio(1); _Pragma("unroll") for (int m = 0; m < 4; ++m) _Pragma("unroll") for (int n = 0; n < 2; ++n) _Pragma("unroll") for (int k = 0; k < 2; ++k) \
;         acc[ai][bj][m][n] = __builtin_amdgcn_mfma_f32_16x16x32_bf16(Bt[n][k], At[m][k], acc[ai][bj][m][n], 0, 0, 0); __builtin_amdgcn_s_setprio(0); } while (0)
; #define PG8_WAIT_V(n) asm volatile("s_waitcnt vmcnt(" #n ")" ::: "memory")
; #define PG8_WAIT_L(n) asm volatile("s_waitcnt lgkmcnt(" #n ")" ::: "memory")
; #define PG8_BAR __builtin_amdgcn_s_barrier()
; #define PG8_SCHED __builtin_amdgcn_sched_barrier(0)
; template <class Epi, class Sched, bool ALIGN_EPI = false, bool SP2 = false>
; __device__ __forceinline__ void gemm_phase(PG8_LAS unsigned char* lds, const Gemm g, const Sched& S, const Epi& E) {
;     ...
;         for (int t = 0; t < nt; t += 2) {
;     ...
;             PG8_WAIT_V(8); PG8_WAIT_L(0); PG8_BAR; PG8_MMA(0, 0, At, B0); PG8_MMA(0, 1, At, B1); PG8_BAR; PG8_SCHED;
;             PG8_LDA(At, 1, 1); PG8_STAGE(PG8_SB(1, 0), b3, voffB); PG8_STAGE(PG8_SB(1, 1), b3 + hstep, voffB); PG8_STAGE(PG8_SA(1, 0), a3, voffA);
;             PG8_WAIT_V(8); PG8_WAIT_L(0); PG8_BAR; PG8_MMA(1, 0, At, B0); PG8_MMA(1, 1, At, B1); PG8_BAR; PG8_SCHED;
	s_add_i32 s43, s43, s50
	v_lshl_add_u64 v[226:227], v[226:227], 0, s[20:21]
	s_mov_b32 m0, s43
	ds_read_b128 v[162:165], v220 offset:49152
	ds_read_b128 v[166:169], v220 offset:50176
	ds_read_b128 v[170:173], v220 offset:51200
	ds_read_b128 v[196:199], v220 offset:52224
	ds_read_b128 v[200:203], v220 offset:53248
	ds_read_b128 v[204:207], v220 offset:54272
	ds_read_b128 v[208:211], v220 offset:55296
	ds_read_b128 v[212:215], v220 offset:56320
	global_load_lds_dwordx4 v[226:227], off
	s_add_i32 m0, s43, 0x2000
	s_add_u32 s6, s6, 0x40080
	v_lshl_add_u64 v[226:227], v[228:229], 0, s[20:21]
	s_addc_u32 s7, s7, 0
	s_add_i32 s43, s46, s50
	global_load_lds_dwordx4 v[226:227], off
	v_lshl_add_u64 v[226:227], s[6:7], 0, v[178:179]
	s_mov_b32 m0, s43
	s_nop 0
	global_load_lds_dwordx4 v[226:227], off
	v_lshl_add_u64 v[226:227], s[6:7], 0, v[182:183]
	s_add_i32 m0, s43, 0x2000
	s_nop 0
	global_load_lds_dwordx4 v[226:227], off
	v_lshl_add_u64 v[226:227], v[230:231], 0, s[20:21]
	s_mov_b32 m0, s67
	s_nop 0
	global_load_lds_dwordx4 v[226:227], off
	v_lshl_add_u64 v[226:227], v[232:233], 0, s[20:21]
	s_mov_b32 m0, s68
	s_nop 0
	global_load_lds_dwordx4 v[226:227], off
	s_waitcnt vmcnt(8)
	s_waitcnt lgkmcnt(0)
	s_barrier
	s_setprio 1
	s_waitcnt lgkmcnt(0)
	v_mfma_f32_16x16x32_bf16 v[62:65], v[130:133], v[162:165], v[62:65]
	v_mfma_f32_16x16x32_bf16 v[58:61], v[138:141], v[162:165], v[58:61]
	v_mfma_f32_16x16x32_bf16 v[46:49], v[130:133], v[170:173], v[46:49]
	v_mfma_f32_16x16x32_bf16 v[42:45], v[138:141], v[170:173], v[42:45]
	v_mfma_f32_16x16x32_bf16 v[30:33], v[130:133], v[200:203], v[30:33]
	v_mfma_f32_16x16x32_bf16 v[26:29], v[138:141], v[200:203], v[26:29]
	v_mfma_f32_16x16x32_bf16 v[14:17], v[130:133], v[208:211], v[14:17]
	v_mfma_f32_16x16x32_bf16 v[10:13], v[138:141], v[208:211], v[10:13]
	v_mfma_f32_16x16x32_bf16 v[62:65], v[134:137], v[166:169], v[62:65]
	v_mfma_f32_16x16x32_bf16 v[58:61], v[142:145], v[166:169], v[58:61]
	v_mfma_f32_16x16x32_bf16 v[46:49], v[134:137], v[196:199], v[46:49]
	v_mfma_f32_16x16x32_bf16 v[42:45], v[142:145], v[196:199], v[42:45]
	v_mfma_f32_16x16x32_bf16 v[30:33], v[134:137], v[204:207], v[30:33]
	v_mfma_f32_16x16x32_bf16 v[26:29], v[142:145], v[204:207], v[26:29]
	v_mfma_f32_16x16x32_bf16 v[14:17], v[134:137], v[212:215], v[14:17]
	v_mfma_f32_16x16x32_bf16 v[10:13], v[142:145], v[212:215], v[10:13]
	v_mfma_f32_16x16x32_bf16 v[54:57], v[146:149], v[162:165], v[54:57]
	v_mfma_f32_16x16x32_bf16 v[50:53], v[154:157], v[162:165], v[50:53]
	v_mfma_f32_16x16x32_bf16 v[38:41], v[146:149], v[170:173], v[38:41]
	v_mfma_f32_16x16x32_bf16 v[34:37], v[154:157], v[170:173], v[34:37]
	v_mfma_f32_16x16x32_bf16 v[22:25], v[146:149], v[200:203], v[22:25]
	v_mfma_f32_16x16x32_bf16 v[18:21], v[154:157], v[200:203], v[18:21]
	v_mfma_f32_16x16x32_bf16 v[6:9], v[146:149], v[208:211], v[6:9]
	v_mfma_f32_16x16x32_bf16 v[2:5], v[154:157], v[208:211], v[2:5]
	v_mfma_f32_16x16x32_bf16 v[54:57], v[150:153], v[166:169], v[54:57]
	v_mfma_f32_16x16x32_bf16 v[50:53], v[158:161], v[166:169], v[50:53]
	v_mfma_f32_16x16x32_bf16 v[38:41], v[150:153], v[196:199], v[38:41]
	v_mfma_f32_16x16x32_bf16 v[34:37], v[158:161], v[196:199], v[34:37]
	v_mfma_f32_16x16x32_bf16 v[22:25], v[150:153], v[204:207], v[22:25]
	v_mfma_f32_16x16x32_bf16 v[18:21], v[158:161], v[204:207], v[18:21]
	v_mfma_f32_16x16x32_bf16 v[6:9], v[150:153], v[212:215], v[6:9]
	v_mfma_f32_16x16x32_bf16 v[2:5], v[158:161], v[212:215], v[2:5]
	s_setprio 0
	s_barrier
	s_add_i32 s37, s37, 2
	s_add_u32 s4, s4, 0x100
	s_addc_u32 s5, s5, 0
	s_add_u32 s33, s33, 0x100
	s_addc_u32 s35, s35, 0
	s_cmp_gt_u32 s37, 13
	s_cbranch_scc0 .LBB0_411
	s_and_b64 vcc, exec, s[22:23]
	s_cbranch_vccz .LBB0_414
	s_barrier

; #define PG8_STAGE(bufoff, gbase, voff) do { _Pragma("unroll") for (int _i = 0; _i < 2; ++_i) \
;         __builtin_amdgcn_global_load_lds((const unsigned*)((const char*)(gbase) + (voff)[_i]), (PG8_LAS unsigned*)(lds + (bufoff) + ldsw + _i * 8192), 16, 0, 0); } while (0)
; #define PG8_LDA(dst, b, h) do { _Pragma("unroll") for (int m = 0; m < 4; ++m) _Pragma("unroll") for (int k = 0; k < 2; ++k) dst[m][k] = *(const PG8_LAS bf16x8*)(lds + PG8_SA(b, h) + aoff + m * 2048 + k * 1024); } while (0)
; #define PG8_LDB(dst, b, h) do { _Pragma("unroll") for (int n = 0; n < 2; ++n) _Pragma("unroll") for (int k = 0; k < 2; ++k) dst[n][k] = *(const PG8_LAS bf16x8*)(lds + PG8_SB(b, h) + boff + n * 2048 + k * 1024); } while (0)
; #define PG8_MMA(ai, bj, At, Bt) do { __builtin_amdgcn_s_setprio(1); _Pragma("unroll") for (int m = 0; m < 4; ++m) _Pragma("unroll") for (int n = 0; n < 2; ++n) _Pragma("unroll") for (int k = 0; k < 2; ++k) \
;         acc[ai][bj][m][n] = __builtin_amdgcn_mfma_f32_16x16x32_bf16(Bt[n][k], At[m][k], acc[ai][bj][m][n], 0, 0, 0); __builtin_amdgcn_s_setprio(0); } while (0)
; #define PG8_WAIT_V(n) asm volatile("s_waitcnt vmcnt(" #n ")" ::: "memory")
; #define PG8_WAIT_L(n) asm volatile("s_waitcnt lgkmcnt(" #n ")" ::: "memory")
; #define PG8_BAR __builtin_amdgcn_s_barrier()
; #define PG8_SCHED __builtin_amdgcn_sched_barrier(0)
; template <class Epi, class Sched, bool ALIGN_EPI = false, bool SP2 = false>
; __device__ __forceinline__ void gemm_phase(PG8_LAS unsigned char* lds, const Gemm g, const Sched& S, const Epi& E) {
;     ...
;             PG8_LDB(B0, 0, 0); PG8_LDB(B1, 0, 1); PG8_SCHED; PG8_LDA(At, 0, 0); PG8_STAGE(PG8_SA(1, 1), a1 + hstep, voffA);
;             PG8_WAIT_V(8); PG8_WAIT_L(0); PG8_BAR; PG8_MMA(0, 0, At, B0); PG8_MMA(0, 1, At, B1); PG8_BAR; PG8_SCHED;
;             PG8_LDA(At, 0, 1); PG8_STAGE(PG8_SB(0, 0), b2, voffB); PG8_STAGE(PG8_SB(0, 1), b2 + hstep, voffB); PG8_STAGE(PG8_SA(0, 0), a2, voffA);
;             PG8_WAIT_V(8); PG8_WAIT_L(0); PG8_BAR; PG8_MMA(1, 0, At, B0); PG8_MMA(1, 1, At, B1); PG8_BAR; PG8_SCHED;
.LBB0_1236:
	ds_read_b128 v[128:131], v175
	ds_read_b128 v[132:135], v175 offset:1024
	ds_read_b128 v[136:139], v175 offset:2048
	ds_read_b128 v[140:143], v175 offset:3072
	ds_read_b128 v[144:147], v176
	ds_read_b128 v[148:151], v176 offset:1024
	ds_read_b128 v[164:167], v176 offset:2048
	ds_read_b128 v[168:171], v176 offset:3072
	s_add_u32 s24, s22, 0xfffc0080
	s_addc_u32 s25, s23, -1
	s_cmp_eq_u32 s61, 12
	s_cselect_b32 s27, s5, s25
	s_cselect_b32 s26, s6, s24
	s_cselect_b32 s25, s15, s60
	s_cselect_b32 s24, s17, s59
	v_lshl_add_u64 v[210:211], s[22:23], 0, v[156:157]
	s_add_i32 m0, s36, 0xc000
	ds_read_b128 v[178:181], v177
	ds_read_b128 v[182:185], v177 offset:1024
	ds_read_b128 v[186:189], v177 offset:2048
	ds_read_b128 v[190:193], v177 offset:3072
	ds_read_b128 v[194:197], v177 offset:4096
	ds_read_b128 v[198:201], v177 offset:5120
	ds_read_b128 v[202:205], v177 offset:6144
	ds_read_b128 v[206:209], v177 offset:7168
	global_load_lds_dwordx4 v[210:211], off
	v_lshl_add_u64 v[210:211], s[22:23], 0, v[158:159]
	s_add_i32 m0, s36, 0xe000
	s_nop 0
	global_load_lds_dwordx4 v[210:211], off
	s_waitcnt vmcnt(8)
	s_waitcnt lgkmcnt(0)
	s_barrier
	s_setprio 1
	s_waitcnt lgkmcnt(0)
	v_mfma_f32_16x16x32_bf16 v[124:127], v[128:131], v[178:181], v[124:127]
	v_mfma_f32_16x16x32_bf16 v[120:123], v[136:139], v[178:181], v[120:123]
	v_mfma_f32_16x16x32_bf16 v[108:111], v[128:131], v[186:189], v[108:111]
	v_mfma_f32_16x16x32_bf16 v[104:107], v[136:139], v[186:189], v[104:107]
	v_mfma_f32_16x16x32_bf16 v[92:95], v[128:131], v[194:197], v[92:95]
	v_mfma_f32_16x16x32_bf16 v[88:91], v[136:139], v[194:197], v[88:91]
	v_mfma_f32_16x16x32_bf16 v[76:79], v[128:131], v[202:205], v[76:79]
	v_mfma_f32_16x16x32_bf16 v[72:75], v[136:139], v[202:205], v[72:75]
	v_mfma_f32_16x16x32_bf16 v[124:127], v[132:135], v[182:185], v[124:127]
	v_mfma_f32_16x16x32_bf16 v[120:123], v[140:143], v[182:185], v[120:123]
	v_mfma_f32_16x16x32_bf16 v[108:111], v[132:135], v[190:193], v[108:111]
	v_mfma_f32_16x16x32_bf16 v[104:107], v[140:143], v[190:193], v[104:107]
	v_mfma_f32_16x16x32_bf16 v[92:95], v[132:135], v[198:201], v[92:95]
	v_mfma_f32_16x16x32_bf16 v[88:91], v[140:143], v[198:201], v[88:91]
	v_mfma_f32_16x16x32_bf16 v[76:79], v[132:135], v[206:209], v[76:79]
	v_mfma_f32_16x16x32_bf16 v[72:75], v[140:143], v[206:209], v[72:75]
	v_mfma_f32_16x16x32_bf16 v[116:119], v[144:147], v[178:181], v[116:119]
	v_mfma_f32_16x16x32_bf16 v[112:115], v[164:167], v[178:181], v[112:115]
	v_mfma_f32_16x16x32_bf16 v[100:103], v[144:147], v[186:189], v[100:103]
	v_mfma_f32_16x16x32_bf16 v[96:99], v[164:167], v[186:189], v[96:99]
	v_mfma_f32_16x16x32_bf16 v[84:87], v[144:147], v[194:197], v[84:87]
	v_mfma_f32_16x16x32_bf16 v[80:83], v[164:167], v[194:197], v[80:83]
	v_mfma_f32_16x16x32_bf16 v[68:71], v[144:147], v[202:205], v[68:71]
	v_mfma_f32_16x16x32_bf16 v[64:67], v[164:167], v[202:205], v[64:67]
	v_mfma_f32_16x16x32_bf16 v[116:119], v[148:151], v[182:185], v[116:119]
	v_mfma_f32_16x16x32_bf16 v[112:115], v[168:171], v[182:185], v[112:115]
	v_mfma_f32_16x16x32_bf16 v[100:103], v[148:151], v[190:193], v[100:103]
	v_mfma_f32_16x16x32_bf16 v[96:99], v[168:171], v[190:193], v[96:99]
	v_mfma_f32_16x16x32_bf16 v[84:87], v[148:151], v[198:201], v[84:87]
	v_mfma_f32_16x16x32_bf16 v[80:83], v[168:171], v[198:201], v[80:83]
	v_mfma_f32_16x16x32_bf16 v[68:71], v[148:151], v[206:209], v[68:71]
	v_mfma_f32_16x16x32_bf16 v[64:67], v[168:171], v[206:209], v[64:67]
	s_setprio 0
	s_barrier
	s_add_i32 s62, s52, s34
	v_lshl_add_u64 v[210:211], s[24:25], 0, v[152:153]
	s_mov_b32 m0, s62
	ds_read_b128 v[178:181], v177 offset:16384
	ds_read_b128 v[182:185], v177 offset:17408
	ds_read_b128 v[186:189], v177 offset:18432
	ds_read_b128 v[190:193], v177 offset:19456
	ds_read_b128 v[194:197], v177 offset:20480
	ds_read_b128 v[198:201], v177 offset:21504
	ds_read_b128 v[202:205], v177 offset:22528
	ds_read_b128 v[206:209], v177 offset:23552
	global_load_lds_dwordx4 v[210:211], off
	s_add_i32 m0, s62, 0x2000
	s_add_u32 s62, s24, 0x40000
	v_lshl_add_u64 v[212:213], s[24:25], 0, v[154:155]
	s_addc_u32 s63, s25, 0
	s_add_i32 s64, s53, s34
	global_load_lds_dwordx4 v[212:213], off
	v_lshl_add_u64 v[214:215], s[62:63], 0, v[152:153]
	s_mov_b32 m0, s64
	v_lshl_add_u64 v[216:217], s[26:27], 0, v[154:155]
	global_load_lds_dwordx4 v[214:215], off
	v_lshl_add_u64 v[214:215], s[62:63], 0, v[154:155]
	s_add_i32 m0, s64, 0x2000
	s_nop 0
	global_load_lds_dwordx4 v[214:215], off
	v_lshl_add_u64 v[214:215], s[26:27], 0, v[152:153]
	s_mov_b32 m0, s36
	s_nop 0
	global_load_lds_dwordx4 v[214:215], off
	s_mov_b32 m0, s37
	s_nop 0
	global_load_lds_dwordx4 v[216:217], off
	s_waitcnt vmcnt(8)
	s_waitcnt lgkmcnt(0)
	s_barrier
; #define PG8_STAGE(bufoff, gbase, voff) do { _Pragma("unroll") for (int _i = 0; _i < 2; ++_i) \
;         __builtin_amdgcn_global_load_lds((const unsigned*)((const char*)(gbase) + (voff)[_i]), (PG8_LAS unsigned*)(lds + (bufoff) + ldsw + _i * 8192), 16, 0, 0); } while (0)
; #define PG8_LDA(dst, b, h) do { _Pragma("unroll") for (int m = 0; m < 4; ++m) _Pragma("unroll") for (int k = 0; k < 2; ++k) dst[m][k] = *(const PG8_LAS bf16x8*)(lds + PG8_SA(b, h) + aoff + m * 2048 + k * 1024); } while (0)
; #define PG8_LDB(dst, b, h) do { _Pragma("unroll") for (int n = 0; n < 2; ++n) _Pragma("unroll") for (int k = 0; k < 2; ++k) dst[n][k] = *(const PG8_LAS bf16x8*)(lds + PG8_SB(b, h) + boff + n * 2048 + k * 1024); } while (0)
; #define PG8_MMA(ai, bj, At, Bt) do { __builtin_amdgcn_s_setprio(1); _Pragma("unroll") for (int m = 0; m < 4; ++m) _Pragma("unroll") for (int n = 0; n < 2; ++n) _Pragma("unroll") for (int k = 0; k < 2; ++k) \
;         acc[ai][bj][m][n] = __builtin_amdgcn_mfma_f32_16x16x32_bf16(Bt[n][k], At[m][k], acc[ai][bj][m][n], 0, 0, 0); __builtin_amdgcn_s_setprio(0); } while (0)
; #define PG8_WAIT_V(n) asm volatile("s_waitcnt vmcnt(" #n ")" ::: "memory")
; #define PG8_WAIT_L(n) asm volatile("s_waitcnt lgkmcnt(" #n ")" ::: "memory")
; #define PG8_BAR __builtin_amdgcn_s_barrier()
; #define PG8_SCHED __builtin_amdgcn_sched_barrier(0)
; template <class Epi, class Sched, bool ALIGN_EPI = false, bool SP2 = false>
; __device__ __forceinline__ void gemm_phase(PG8_LAS unsigned char* lds, const Gemm g, const Sched& S, const Epi& E) {
;     ...
;             PG8_WAIT_V(8); PG8_WAIT_L(0); PG8_BAR; PG8_MMA(1, 0, At, B0); PG8_MMA(1, 1, At, B1); PG8_BAR; PG8_SCHED;
;             PG8_LDB(B0, 1, 0); PG8_LDB(B1, 1, 1); PG8_SCHED; PG8_LDA(At, 1, 0); PG8_STAGE(PG8_SA(0, 1), a2 + hstep, voffA);
;             PG8_WAIT_V(8); PG8_WAIT_L(0); PG8_BAR; PG8_MMA(0, 0, At, B0); PG8_MMA(0, 1, At, B1); PG8_BAR; PG8_SCHED;
	s_setprio 1
	s_waitcnt lgkmcnt(0)
	v_mfma_f32_16x16x32_bf16 v[60:63], v[128:131], v[178:181], v[60:63]
	v_mfma_f32_16x16x32_bf16 v[56:59], v[136:139], v[178:181], v[56:59]
	v_mfma_f32_16x16x32_bf16 v[44:47], v[128:131], v[186:189], v[44:47]
	v_mfma_f32_16x16x32_bf16 v[40:43], v[136:139], v[186:189], v[40:43]
	v_mfma_f32_16x16x32_bf16 v[28:31], v[128:131], v[194:197], v[28:31]
	v_mfma_f32_16x16x32_bf16 v[24:27], v[136:139], v[194:197], v[24:27]
	v_mfma_f32_16x16x32_bf16 v[12:15], v[128:131], v[202:205], v[12:15]
	v_mfma_f32_16x16x32_bf16 v[8:11], v[136:139], v[202:205], v[8:11]
	v_mfma_f32_16x16x32_bf16 v[60:63], v[132:135], v[182:185], v[60:63]
	v_mfma_f32_16x16x32_bf16 v[56:59], v[140:143], v[182:185], v[56:59]
	v_mfma_f32_16x16x32_bf16 v[44:47], v[132:135], v[190:193], v[44:47]
	v_mfma_f32_16x16x32_bf16 v[40:43], v[140:143], v[190:193], v[40:43]
	v_mfma_f32_16x16x32_bf16 v[28:31], v[132:135], v[198:201], v[28:31]
	v_mfma_f32_16x16x32_bf16 v[24:27], v[140:143], v[198:201], v[24:27]
	v_mfma_f32_16x16x32_bf16 v[12:15], v[132:135], v[206:209], v[12:15]
	v_mfma_f32_16x16x32_bf16 v[8:11], v[140:143], v[206:209], v[8:11]
	v_mfma_f32_16x16x32_bf16 v[52:55], v[144:147], v[178:181], v[52:55]
	v_mfma_f32_16x16x32_bf16 v[48:51], v[164:167], v[178:181], v[48:51]
	v_mfma_f32_16x16x32_bf16 v[36:39], v[144:147], v[186:189], v[36:39]
	v_mfma_f32_16x16x32_bf16 v[32:35], v[164:167], v[186:189], v[32:35]
	v_mfma_f32_16x16x32_bf16 v[20:23], v[144:147], v[194:197], v[20:23]
	v_mfma_f32_16x16x32_bf16 v[16:19], v[164:167], v[194:197], v[16:19]
	v_mfma_f32_16x16x32_bf16 v[4:7], v[144:147], v[202:205], v[4:7]
	v_mfma_f32_16x16x32_bf16 v[0:3], v[164:167], v[202:205], v[0:3]
	v_mfma_f32_16x16x32_bf16 v[52:55], v[148:151], v[182:185], v[52:55]
	v_mfma_f32_16x16x32_bf16 v[48:51], v[168:171], v[182:185], v[48:51]
	v_mfma_f32_16x16x32_bf16 v[36:39], v[148:151], v[190:193], v[36:39]
	v_mfma_f32_16x16x32_bf16 v[32:35], v[168:171], v[190:193], v[32:35]
	v_mfma_f32_16x16x32_bf16 v[20:23], v[148:151], v[198:201], v[20:23]
	v_mfma_f32_16x16x32_bf16 v[16:19], v[168:171], v[198:201], v[16:19]
	v_mfma_f32_16x16x32_bf16 v[4:7], v[148:151], v[206:209], v[4:7]
	v_mfma_f32_16x16x32_bf16 v[0:3], v[168:171], v[206:209], v[0:3]
	s_setprio 0
	s_barrier
	s_add_i32 s62, 0, 0x18000
	s_add_i32 s63, 0, 0x1c000
	v_add_u32_e32 v140, s62, v174
	v_add_u32_e32 v168, s63, v174
	ds_read_b128 v[128:131], v140
	ds_read_b128 v[132:135], v140 offset:1024
	ds_read_b128 v[136:139], v140 offset:2048
	ds_read_b128 v[140:143], v140 offset:3072
	ds_read_b128 v[144:147], v168
	ds_read_b128 v[148:151], v168 offset:1024
	ds_read_b128 v[164:167], v168 offset:2048
	ds_read_b128 v[168:171], v168 offset:3072
	s_add_u32 s26, s26, 0x40000
	s_addc_u32 s27, s27, 0
	s_mov_b32 m0, s38
	v_lshl_add_u64 v[218:219], s[26:27], 0, v[152:153]
	ds_read_b128 v[178:181], v177 offset:32768
	ds_read_b128 v[182:185], v177 offset:33792
	ds_read_b128 v[186:189], v177 offset:34816
	ds_read_b128 v[190:193], v177 offset:35840
	ds_read_b128 v[194:197], v177 offset:36864
	ds_read_b128 v[198:201], v177 offset:37888
	ds_read_b128 v[202:205], v177 offset:38912
	ds_read_b128 v[206:209], v177 offset:39936
	global_load_lds_dwordx4 v[218:219], off
	v_lshl_add_u64 v[218:219], s[26:27], 0, v[154:155]
	s_mov_b32 m0, s39
	s_nop 0
	global_load_lds_dwordx4 v[218:219], off
	s_waitcnt vmcnt(8)
	s_waitcnt lgkmcnt(0)
	s_barrier
	s_setprio 1
	s_waitcnt lgkmcnt(0)
	v_mfma_f32_16x16x32_bf16 v[124:127], v[128:131], v[178:181], v[124:127]
	v_mfma_f32_16x16x32_bf16 v[120:123], v[136:139], v[178:181], v[120:123]
	v_mfma_f32_16x16x32_bf16 v[108:111], v[128:131], v[186:189], v[108:111]
	v_mfma_f32_16x16x32_bf16 v[104:107], v[136:139], v[186:189], v[104:107]
	v_mfma_f32_16x16x32_bf16 v[92:95], v[128:131], v[194:197], v[92:95]
	v_mfma_f32_16x16x32_bf16 v[88:91], v[136:139], v[194:197], v[88:91]
	v_mfma_f32_16x16x32_bf16 v[76:79], v[128:131], v[202:205], v[76:79]
	v_mfma_f32_16x16x32_bf16 v[72:75], v[136:139], v[202:205], v[72:75]
	v_mfma_f32_16x16x32_bf16 v[124:127], v[132:135], v[182:185], v[124:127]
	v_mfma_f32_16x16x32_bf16 v[120:123], v[140:143], v[182:185], v[120:123]
	v_mfma_f32_16x16x32_bf16 v[108:111], v[132:135], v[190:193], v[108:111]
	v_mfma_f32_16x16x32_bf16 v[104:107], v[140:143], v[190:193], v[104:107]
	v_mfma_f32_16x16x32_bf16 v[92:95], v[132:135], v[198:201], v[92:95]
	v_mfma_f32_16x16x32_bf16 v[88:91], v[140:143], v[198:201], v[88:91]
	v_mfma_f32_16x16x32_bf16 v[76:79], v[132:135], v[206:209], v[76:79]
	v_mfma_f32_16x16x32_bf16 v[72:75], v[140:143], v[206:209], v[72:75]
	v_mfma_f32_16x16x32_bf16 v[116:119], v[144:147], v[178:181], v[116:119]
	v_mfma_f32_16x16x32_bf16 v[112:115], v[164:167], v[178:181], v[112:115]
	v_mfma_f32_16x16x32_bf16 v[100:103], v[144:147], v[186:189], v[100:103]
	v_mfma_f32_16x16x32_bf16 v[96:99], v[164:167], v[186:189], v[96:99]
	v_mfma_f32_16x16x32_bf16 v[84:87], v[144:147], v[194:197], v[84:87]
	v_mfma_f32_16x16x32_bf16 v[80:83], v[164:167], v[194:197], v[80:83]
	v_mfma_f32_16x16x32_bf16 v[68:71], v[144:147], v[202:205], v[68:71]
	v_mfma_f32_16x16x32_bf16 v[64:67], v[164:167], v[202:205], v[64:67]
	v_mfma_f32_16x16x32_bf16 v[116:119], v[148:151], v[182:185], v[116:119]
	v_mfma_f32_16x16x32_bf16 v[112:115], v[168:171], v[182:185], v[112:115]
	v_mfma_f32_16x16x32_bf16 v[100:103], v[148:151], v[190:193], v[100:103]
	v_mfma_f32_16x16x32_bf16 v[96:99], v[168:171], v[190:193], v[96:99]
	v_mfma_f32_16x16x32_bf16 v[84:87], v[148:151], v[198:201], v[84:87]
	v_mfma_f32_16x16x32_bf16 v[80:83], v[168:171], v[198:201], v[80:83]
	v_mfma_f32_16x16x32_bf16 v[68:71], v[148:151], v[206:209], v[68:71]
	v_mfma_f32_16x16x32_bf16 v[64:67], v[168:171], v[206:209], v[64:67]
	s_setprio 0
	s_barrier
; #define PG8_STAGE(bufoff, gbase, voff) do { _Pragma("unroll") for (int _i = 0; _i < 2; ++_i) \
;         __builtin_amdgcn_global_load_lds((const unsigned*)((const char*)(gbase) + (voff)[_i]), (PG8_LAS unsigned*)(lds + (bufoff) + ldsw + _i * 8192), 16, 0, 0); } while (0)
; #define PG8_LDA(dst, b, h) do { _Pragma("unroll") for (int m = 0; m < 4; ++m) _Pragma("unroll") for (int k = 0; k < 2; ++k) dst[m][k] = *(const PG8_LAS bf16x8*)(lds + PG8_SA(b, h) + aoff + m * 2048 + k * 1024); } while (0)
; #define PG8_MMA(ai, bj, At, Bt) do { __builtin_amdgcn_s_setprio(1); _Pragma("unroll") for (int m = 0; m < 4; ++m) _Pragma("unroll") for (int n = 0; n < 2; ++n) _Pragma("unroll") for (int k = 0; k < 2; ++k) \
;         acc[ai][bj][m][n] = __builtin_amdgcn_mfma_f32_16x16x32_bf16(Bt[n][k], At[m][k], acc[ai][bj][m][n], 0, 0, 0); __builtin_amdgcn_s_setprio(0); } while (0)
; #define PG8_WAIT_V(n) asm volatile("s_waitcnt vmcnt(" #n ")" ::: "memory")
; #define PG8_WAIT_L(n) asm volatile("s_waitcnt lgkmcnt(" #n ")" ::: "memory")
; #define PG8_BAR __builtin_amdgcn_s_barrier()
; #define PG8_SCHED __builtin_amdgcn_sched_barrier(0)
; template <class Epi, class Sched, bool ALIGN_EPI = false, bool SP2 = false>
; __device__ __forceinline__ void gemm_phase(PG8_LAS unsigned char* lds, const Gemm g, const Sched& S, const Epi& E) {
;     ...
;         for (int t = 0; t < nt; t += 2) {
;     ...
;             PG8_WAIT_V(8); PG8_WAIT_L(0); PG8_BAR; PG8_MMA(0, 0, At, B0); PG8_MMA(0, 1, At, B1); PG8_BAR; PG8_SCHED;
;             PG8_LDA(At, 1, 1); PG8_STAGE(PG8_SB(1, 0), b3, voffB); PG8_STAGE(PG8_SB(1, 1), b3 + hstep, voffB); PG8_STAGE(PG8_SA(1, 0), a3, voffA);
;             PG8_WAIT_V(8); PG8_WAIT_L(0); PG8_BAR; PG8_MMA(1, 0, At, B0); PG8_MMA(1, 1, At, B1); PG8_BAR; PG8_SCHED;
	s_add_i32 s26, s62, s34
	v_lshl_add_u64 v[210:211], v[210:211], 0, s[10:11]
	s_mov_b32 m0, s26
	ds_read_b128 v[178:181], v177 offset:49152
	ds_read_b128 v[182:185], v177 offset:50176
	ds_read_b128 v[186:189], v177 offset:51200
	ds_read_b128 v[190:193], v177 offset:52224
	ds_read_b128 v[194:197], v177 offset:53248
	ds_read_b128 v[198:201], v177 offset:54272
	ds_read_b128 v[202:205], v177 offset:55296
	ds_read_b128 v[206:209], v177 offset:56320
	global_load_lds_dwordx4 v[210:211], off
	s_add_i32 m0, s26, 0x2000
	s_add_u32 s24, s24, 0x40080
	v_lshl_add_u64 v[210:211], v[212:213], 0, s[10:11]
	s_addc_u32 s25, s25, 0
	s_add_i32 s26, s63, s34
	global_load_lds_dwordx4 v[210:211], off
	v_lshl_add_u64 v[210:211], s[24:25], 0, v[152:153]
	s_mov_b32 m0, s26
	s_nop 0
	global_load_lds_dwordx4 v[210:211], off
	v_lshl_add_u64 v[210:211], s[24:25], 0, v[154:155]
	s_add_i32 m0, s26, 0x2000
	s_nop 0
	global_load_lds_dwordx4 v[210:211], off
	v_lshl_add_u64 v[210:211], v[214:215], 0, s[10:11]
	s_mov_b32 m0, s45
	s_nop 0
	global_load_lds_dwordx4 v[210:211], off
	v_lshl_add_u64 v[210:211], v[216:217], 0, s[10:11]
	s_mov_b32 m0, s46
	s_nop 0
	global_load_lds_dwordx4 v[210:211], off
	s_waitcnt vmcnt(8)
	s_waitcnt lgkmcnt(0)
	s_barrier
	s_setprio 1
	s_waitcnt lgkmcnt(0)
	v_mfma_f32_16x16x32_bf16 v[60:63], v[128:131], v[178:181], v[60:63]
	v_mfma_f32_16x16x32_bf16 v[56:59], v[136:139], v[178:181], v[56:59]
	v_mfma_f32_16x16x32_bf16 v[44:47], v[128:131], v[186:189], v[44:47]
	v_mfma_f32_16x16x32_bf16 v[40:43], v[136:139], v[186:189], v[40:43]
	v_mfma_f32_16x16x32_bf16 v[28:31], v[128:131], v[194:197], v[28:31]
	v_mfma_f32_16x16x32_bf16 v[24:27], v[136:139], v[194:197], v[24:27]
	v_mfma_f32_16x16x32_bf16 v[12:15], v[128:131], v[202:205], v[12:15]
	v_mfma_f32_16x16x32_bf16 v[8:11], v[136:139], v[202:205], v[8:11]
	v_mfma_f32_16x16x32_bf16 v[60:63], v[132:135], v[182:185], v[60:63]
	v_mfma_f32_16x16x32_bf16 v[56:59], v[140:143], v[182:185], v[56:59]
	v_mfma_f32_16x16x32_bf16 v[44:47], v[132:135], v[190:193], v[44:47]
	v_mfma_f32_16x16x32_bf16 v[40:43], v[140:143], v[190:193], v[40:43]
	v_mfma_f32_16x16x32_bf16 v[28:31], v[132:135], v[198:201], v[28:31]
	v_mfma_f32_16x16x32_bf16 v[24:27], v[140:143], v[198:201], v[24:27]
	v_mfma_f32_16x16x32_bf16 v[12:15], v[132:135], v[206:209], v[12:15]
	v_mfma_f32_16x16x32_bf16 v[8:11], v[140:143], v[206:209], v[8:11]
	v_mfma_f32_16x16x32_bf16 v[52:55], v[144:147], v[178:181], v[52:55]
	v_mfma_f32_16x16x32_bf16 v[48:51], v[164:167], v[178:181], v[48:51]
	v_mfma_f32_16x16x32_bf16 v[36:39], v[144:147], v[186:189], v[36:39]
	v_mfma_f32_16x16x32_bf16 v[32:35], v[164:167], v[186:189], v[32:35]
	v_mfma_f32_16x16x32_bf16 v[20:23], v[144:147], v[194:197], v[20:23]
	v_mfma_f32_16x16x32_bf16 v[16:19], v[164:167], v[194:197], v[16:19]
	v_mfma_f32_16x16x32_bf16 v[4:7], v[144:147], v[202:205], v[4:7]
	v_mfma_f32_16x16x32_bf16 v[0:3], v[164:167], v[202:205], v[0:3]
	v_mfma_f32_16x16x32_bf16 v[52:55], v[148:151], v[182:185], v[52:55]
	v_mfma_f32_16x16x32_bf16 v[48:51], v[168:171], v[182:185], v[48:51]
	v_mfma_f32_16x16x32_bf16 v[36:39], v[148:151], v[190:193], v[36:39]
	v_mfma_f32_16x16x32_bf16 v[32:35], v[168:171], v[190:193], v[32:35]
	v_mfma_f32_16x16x32_bf16 v[20:23], v[148:151], v[198:201], v[20:23]
	v_mfma_f32_16x16x32_bf16 v[16:19], v[168:171], v[198:201], v[16:19]
	v_mfma_f32_16x16x32_bf16 v[4:7], v[148:151], v[206:209], v[4:7]
	v_mfma_f32_16x16x32_bf16 v[0:3], v[168:171], v[206:209], v[0:3]
	s_setprio 0
	s_barrier
	s_add_i32 s61, s61, 2
	s_add_u32 s22, s22, 0x100
	s_addc_u32 s23, s23, 0
	s_add_u32 s59, s59, 0x100
	s_addc_u32 s60, s60, 0
	s_cmp_gt_u32 s61, 13
	s_cbranch_scc0 .LBB0_1236
	s_and_b64 vcc, exec, s[12:13]
	s_cbranch_vccz .LBB0_1239
	s_barrier
